# out-proj(even) sample-row tail tiles folded into in-proj(odd) phase: sample tiles ordered last, tail workgroups rebalanced (4 tiles), no split-K/reduce/extra barrier
# speedup vs baseline: 1.0330x; 1.0266x over previous
; __global__ void __launch_bounds__(NTHR) mega(Params p) {
;     ...
;     if (IN(5)) {
;         pg8::Gemm g{(const bf16_t*)(ws + WS_XB), (const bf16_t*)(ws + WS_WINO), T, 3072, 1024, 1024};
;         pg8::StaticOrder S; S.init(T, 3072, gridDim.x, blockIdx.x);
;         EpiInOdd E{(bf16_t*)(ws + WS_Z2), (const float*)(ws + WS_RSQ1)};
;         pg8::gemm_phase<EpiInOdd, pg8::StaticOrder>(L, g, S, E);
.Lp5_go:
	s_movk_i32 s98, 0xcc
	s_cmpk_eq_i32 s94, 0x100
	s_cselect_b32 s98, 0xc0, s98
	s_cmpk_gt_i32 s2, 0x65f
	v_readfirstlane_b32 s5, v136
	s_cbranch_scc1 .LBB0_841
	v_lshrrev_b32_e32 v0, 5, v136
	v_lshrrev_b32_e32 v2, 1, v136
	v_and_b32_e32 v0, 4, v0
	s_waitcnt lgkmcnt(0)
	v_bfe_u32 v1, v136, 2, 2
	v_and_b32_e32 v11, 24, v2
	v_or3_b32 v0, v0, v1, v11
	v_lshlrev_b32_e32 v1, 4, v136
	v_add_u32_e32 v8, 0x2000, v1
	v_lshrrev_b32_e32 v2, 7, v8
	s_movk_i32 s0, 0xe0
	v_and_b32_e32 v4, 32, v136
	s_add_u32 s3, s44, 0x1a20000
	v_and_or_b32 v3, v2, s0, v0
	v_bitop3_b32 v9, v1, v4, 48 bitop3:0x6c
	v_and_b32_e32 v10, 64, v136
	v_bfe_u32 v12, v136, 2, 4
	s_movk_i32 s0, 0xf0
	s_addc_u32 s33, s45, 0
	v_or_b32_e32 v1, v9, v10
	v_and_or_b32 v2, v2, s0, v12
	s_add_u32 s34, s44, 0x1000000
	v_lshl_or_b32 v130, v2, 11, v1
	v_lshrrev_b32_e32 v2, 3, v136
	s_movk_i32 s0, 0x60
	s_addc_u32 s35, s45, 0
	v_and_or_b32 v0, v2, s0, v0
	s_movk_i32 s0, 0x70
	s_ashr_i32 s37, s2, 31
	v_lshl_or_b32 v132, v0, 11, v1
	v_and_or_b32 v0, v2, s0, v12
	s_lshr_b32 s0, s37, 29
	s_add_i32 s0, s2, s0
	s_lshr_b32 s16, s5, 6
	s_and_b32 s1, s0, -8
	s_lshr_b32 s18, s5, 8
	s_lshl_b32 s36, s16, 10
	s_sub_i32 s1, s2, s1
	s_cmp_lt_i32 s1, 0
	s_movk_i32 s38, 0xcd
	s_cselect_b32 s4, s38, s98
	s_mul_i32 s1, s1, s4
	s_ashr_i32 s0, s0, 3
	s_add_i32 s1, s1, s0
	s_mul_hi_i32 s0, s1, 0x2aaaaaab
	s_lshr_b32 s4, s0, 31
	s_ashr_i32 s0, s0, 4
	s_add_i32 s0, s0, s4
	s_lshl_b32 s6, s0, 3
	s_mulk_i32 s0, 0x60
	s_sub_i32 s0, s1, s0
	s_bfe_i32 s1, s0, 0x80000
	s_bfe_u32 s1, s1, 0x3000c
	s_add_i32 s1, s0, s1
	s_bfe_i32 s4, s1, 0x80000
	s_and_b32 s1, s1, 0xf8
	s_sub_i32 s0, s0, s1
	s_sext_i32_i16 s4, s4
	s_sext_i32_i8 s0, s0
	s_lshr_b32 s4, s4, 3
	s_add_i32 s0, s6, s0
	s_ashr_i32 s1, s0, 31
	s_bfe_i64 s[10:11], s[4:5], 0x100000
	s_lshl_b64 s[6:7], s[0:1], 19
	s_lshl_b64 s[10:11], s[10:11], 19
	s_add_u32 s28, s34, s10
	s_addc_u32 s29, s35, s11
	s_add_i32 s39, s36, 0
	s_add_i32 m0, s39, 0x10000
	v_lshl_or_b32 v128, v3, 11, v1
	global_load_lds_dwordx4 v132, s[28:29]
	s_add_i32 m0, s39, 0x12000
	s_add_u32 s10, s28, 0x40000
	global_load_lds_dwordx4 v128, s[28:29]
	s_addc_u32 s11, s29, 0
	s_add_i32 m0, s39, 0x14000
	v_lshl_or_b32 v134, v0, 11, v1
	global_load_lds_dwordx4 v132, s[10:11]
	s_add_i32 m0, s39, 0x16000
	s_add_u32 s6, s3, s6
	s_addc_u32 s7, s33, s7
	s_add_i32 s48, s39, 0x2000
	global_load_lds_dwordx4 v128, s[10:11]
	s_mov_b32 m0, s39
	s_add_u32 s10, s6, 0x40000
	global_load_lds_dwordx4 v134, s[6:7]
	s_mov_b32 m0, s48
	s_addc_u32 s11, s7, 0
	s_add_i32 s49, s39, 0x4000
	global_load_lds_dwordx4 v130, s[6:7]
	s_mov_b32 m0, s49
	s_add_i32 s50, s39, 0x6000
	global_load_lds_dwordx4 v134, s[10:11]
	s_mov_b32 m0, s50
	v_mov_b32_e32 v133, 0
	global_load_lds_dwordx4 v130, s[10:11]
	v_mov_b32_e32 v129, v133
	v_mov_b32_e32 v135, v133
	v_mov_b32_e32 v131, v133
	s_cmp_eq_u32 s18, 1
	s_mov_b32 s51, 0
	v_lshl_add_u64 v[6:7], s[28:29], 0, v[132:133]
	v_lshl_add_u64 v[4:5], s[28:29], 0, v[128:129]
	v_lshl_add_u64 v[0:1], s[6:7], 0, v[134:135]
	s_cselect_b64 s[10:11], -1, 0
	s_cmp_lg_u32 s18, 1
	v_lshl_add_u64 v[2:3], s[6:7], 0, v[130:131]
	s_cbranch_scc1 .LBB0_828
	s_barrier
.LBB0_828:
	s_add_u32 s12, s44, 0x5f0e000
	s_addc_u32 s13, s45, 0
	s_add_u32 s14, s44, 0x5e42000
	s_addc_u32 s15, s45, 0
	s_lshl_b32 s1, s16, 5
	s_mov_b64 s[16:17], 0x80
	s_and_b32 s22, s1, 0x60
	s_add_i32 m0, s39, 0x18000
	v_lshl_add_u64 v[6:7], v[6:7], 0, s[16:17]
	s_lshl_b32 s19, s18, 13
	s_lshl_b32 s23, s22, 7
	s_waitcnt vmcnt(2)
	s_barrier
	global_load_lds_dwordx4 v[6:7], off
	v_lshl_add_u64 v[4:5], v[4:5], 0, s[16:17]
	s_add_i32 m0, s39, 0x1a000
	s_add_i32 s52, s39, 0x8000
	s_add_i32 s53, s39, 0xa000
	global_load_lds_dwordx4 v[4:5], off
	v_lshl_add_u64 v[0:1], v[0:1], 0, s[16:17]
	s_mov_b32 m0, s52
	s_add_u32 s20, s28, 0x40080
	global_load_lds_dwordx4 v[0:1], off
	v_lshl_add_u64 v[0:1], v[2:3], 0, s[16:17]
	s_mov_b32 m0, s53
	s_addc_u32 s21, s29, 0
	global_load_lds_dwordx4 v[0:1], off
	s_add_i32 m0, s39, 0x1c000
	v_lshl_add_u64 v[0:1], s[20:21], 0, v[132:133]
	global_load_lds_dwordx4 v[0:1], off
	v_lshl_add_u64 v[0:1], s[20:21], 0, v[128:129]
	s_add_i32 m0, s39, 0x1e000
	s_sext_i32_i8 s1, s4
	global_load_lds_dwordx4 v[0:1], off
	v_and_b32_e32 v0, 15, v136
	v_lshlrev_b32_e32 v1, 1, v11
	v_lshlrev_b32_e32 v2, 2, v136
	v_lshlrev_b32_e32 v3, 6, v136
	s_movk_i32 s4, 0x3c0
	v_lshl_or_b32 v137, s18, 6, v0
	v_lshl_or_b32 v0, v0, 6, v1
	v_and_b32_e32 v2, 32, v2
	v_and_or_b32 v1, v3, s4, v1
	v_bitop3_b32 v152, s23, v1, v2 bitop3:0xf6
	v_lshlrev_b32_e32 v1, 8, v136
	v_bitop3_b32 v0, v0, s19, v2 bitop3:0xde
	v_and_b32_e32 v1, 0x38000, v1
	v_lshlrev_b32_e32 v2, 11, v12
	v_or3_b32 v1, v9, v1, v2
	v_add_u32_e32 v138, v1, v10
	v_lshlrev_b32_e32 v1, 4, v8
	s_waitcnt vmcnt(6)
	s_cmpk_lt_u32 s5, 0x100
	v_and_b32_e32 v1, 0x78000, v1
	s_cselect_b64 s[18:19], -1, 0
	v_or3_b32 v1, v9, v1, v2
	s_add_i32 s56, 0, 0x10000
	s_add_i32 s57, 0, 0x14000
	s_ashr_i32 s54, s94, 31
	s_mov_b32 s55, s94
	v_or_b32_e32 v153, s22, v11
	v_mov_b32_e32 v139, v133
	v_add_u32_e32 v140, v1, v10
	v_mov_b32_e32 v141, v133
	s_movk_i32 s30, 0x660
	s_cmpk_eq_i32 s94, 0x100
	s_cbranch_scc0 .Lp5_bound_done
	s_sub_i32 s31, s2, 0x60
	s_cmp_lt_u32 s31, 32
	s_cselect_b32 s30, 0x460, s30
	s_sub_i32 s31, s2, 0x80
	s_cmp_lt_u32 s31, 64
	s_cselect_b32 s30, 0x6c0, s30

;     __device__ __forceinline__ bool next(int i, Unit& u) const {
;         const long Lx = (long)i * G + c; if (Lx >= nrun) return false;
;         map((int)Lx, u); return true;
;     }
.LBB0_831:
	s_add_i32 s51, s51, 1
	s_mul_i32 s4, s51, s54
	s_mul_hi_u32 s5, s51, s55
	s_add_i32 s5, s5, s4
	s_mul_i32 s4, s51, s55
	s_add_u32 s24, s4, s2
	s_addc_u32 s25, s5, s37
	v_cmp_gt_i64_e32 vcc, s[24:25], v[144:145]
	v_cmp_lt_i64_e64 s[4:5], s[24:25], v[142:143]
	s_cbranch_vccnz .LBB0_833
	s_cmpk_lt_i32 s24, 0x660
	s_cbranch_scc1 .Lp5_noremap
	s_cmpk_lt_i32 s24, 0x6a0
	s_movk_i32 s20, 0x240
	s_cselect_b32 s20, 0x120, s20
	s_sub_i32 s24, s24, s20
.Lp5_noremap:
	s_ashr_i32 s20, s24, 31
	s_lshr_b32 s20, s20, 29
	s_add_i32 s20, s24, s20
	s_ashr_i32 s21, s20, 3
	s_and_b32 s20, s20, -8
	s_sub_i32 s20, s24, s20
	s_cmp_lt_i32 s20, 0
	s_cselect_b32 s22, s38, s98
	s_cmpk_lt_i32 s24, 0x600
	s_cbranch_scc1 .Lp5_q_ok
	s_cmpk_eq_i32 s94, 0x100
	s_cbranch_scc0 .Lp5_q_ok
	s_movk_i32 s22, 12
	s_addk_i32 s21, 0x540
.Lp5_q_ok:
	s_mul_i32 s20, s20, s22
	s_add_i32 s20, s20, s21
	s_mul_hi_i32 s21, s20, 0x2aaaaaab
	s_lshr_b32 s22, s21, 31
	s_ashr_i32 s21, s21, 4
	s_add_i32 s21, s21, s22
	s_lshl_b32 s22, s21, 3
	s_sub_i32 s23, 0x88, s22
	s_min_i32 s23, s23, 8
	s_abs_i32 s24, s23
	v_cvt_f32_u32_e32 v0, s24
	s_sub_i32 s26, 0, s24
	s_mulk_i32 s21, 0x60
	s_sub_i32 s21, s20, s21
	v_rcp_iflag_f32_e32 v0, v0
	s_abs_i32 s20, s21
	s_xor_b32 s25, s21, s23
	s_ashr_i32 s25, s25, 31
	v_mul_f32_e32 v0, 0x4f7ffffe, v0
	v_cvt_u32_f32_e32 v0, v0
	s_nop 0
	v_readfirstlane_b32 s27, v0
	s_mul_i32 s26, s26, s27
	s_mul_hi_u32 s26, s27, s26
	s_add_i32 s27, s27, s26
	s_mul_hi_u32 s26, s20, s27
	s_mul_i32 s27, s26, s24
	s_sub_i32 s20, s20, s27
	s_add_i32 s30, s26, 1
	s_sub_i32 s27, s20, s24
	s_cmp_ge_u32 s20, s24
	s_cselect_b32 s26, s30, s26
	s_cselect_b32 s20, s27, s20
	s_add_i32 s27, s26, 1
	s_cmp_ge_u32 s20, s24
	s_cselect_b32 s20, s27, s26
	s_xor_b32 s20, s20, s25
	s_sub_i32 s20, s20, s25
	s_mul_i32 s23, s20, s23
	s_sub_i32 s21, s21, s23
	s_add_i32 s22, s22, s21
	s_cmpk_lt_i32 s22, 0x80
	s_cbranch_scc1 .Lp5_nowait
	s_cmpk_eq_i32 s94, 0x100
	s_cbranch_scc0 .Lp5_nowait
	s_add_u32 s26, s44, 0x1f711800
	s_addc_u32 s27, s45, 0
	v_mov_b32_e32 v0, 0
